# out-proj/MLP-out epilogue: the 8 per-row-group sum-of-squares dword stores merged into 2 full-wave stores (each lane quarter stores one group)
# baseline (speedup 1.0000x reference)
; __device__ __forceinline__ unsigned cvt_pk_bf16(float lo, float hi) { f32x2 v = {lo, hi}; bf16x2_t b = __builtin_convertvector(v, bf16x2_t); return __builtin_bit_cast(unsigned, b); }
;     __device__ __forceinline__ void operator()(const f32x4 (&acc)[2][2][4][2], const Unit& u, int wr, int wc, int fr, int fq) const {
;     ...
;                         const f32x4 v0 = b0 + acc[ai][bj][m][0] * sc, v1 = b1 + acc[ai][bj][m][1] * sc;
;                         if (out != nullptr) { *(f32x4*)(out + off) = v0; *(f32x4*)(out + off + 4) = v1; }
;                         part += (v0[0] * v0[0] + v0[1] * v0[1]) + (v0[2] * v0[2] + v0[3] * v0[3]) + (v1[0] * v1[0] + v1[1] * v1[1]) + (v1[2] * v1[2] + v1[3] * v1[3]);
;                         if (ssq_o1 != nullptr) {
;                             u32x4 w; w.x = cvt_pk_bf16(v0[0], v0[1]); w.y = cvt_pk_bf16(v0[2], v0[3]); w.z = cvt_pk_bf16(v1[0], v1[1]); w.w = cvt_pk_bf16(v1[2], v1[3]);
;                             *(u32x4*)(O + off) = w;
;                         }
;                     }
;                     part += __shfl_xor(part, 16); part += __shfl_xor(part, 32);
;                     if (fq == 0 && ssq_o1 != nullptr) ssq_o1[(size_t)row * 16 + u.pn * 4 + wc] = part;
.LBB0_907:
	v_mul_f32_e32 v117, v117, v117
	v_fmac_f32_e32 v117, v116, v116
	v_mul_f32_e32 v116, v119, v119
	v_mul_f32_e32 v125, v125, v125
	v_fmac_f32_e32 v116, v118, v118
	v_mul_f32_e32 v113, v113, v113
	v_fmac_f32_e32 v125, v124, v124
	v_mul_f32_e32 v124, v127, v127
	v_add_f32_e32 v116, v117, v116
	v_fmac_f32_e32 v113, v112, v112
	v_fmac_f32_e32 v124, v126, v126
	v_mul_f32_e32 v121, v121, v121
	v_add_f32_e32 v112, v113, v116
	v_mul_f32_e32 v113, v115, v115
	v_add_f32_e32 v124, v125, v124
	v_fmac_f32_e32 v121, v120, v120
	v_fmac_f32_e32 v113, v114, v114
	v_and_b32_e32 v114, 64, v206
	v_add_f32_e32 v120, v121, v124
	v_mul_f32_e32 v121, v123, v123
	v_add_f32_e32 v112, v113, v112
	v_xor_b32_e32 v113, 16, v206
	v_add_u32_e32 v114, 64, v114
	v_fmac_f32_e32 v121, v122, v122
	v_cmp_lt_i32_e32 vcc, v113, v114
	v_add_f32_e32 v120, v121, v120
	v_add_f32_e32 v112, v120, v112
	v_cndmask_b32_e32 v113, v206, v113, vcc
	v_lshlrev_b32_e32 v118, 2, v113
	ds_bpermute_b32 v113, v118, v112
	v_xor_b32_e32 v115, 32, v206
	v_cmp_lt_i32_e32 vcc, v115, v114
	s_lshl_b32 s6, s27, 2
	s_ashr_i32 s7, s6, 31
	v_cndmask_b32_e32 v114, v206, v115, vcc
	v_lshlrev_b32_e32 v119, 2, v114
	s_waitcnt lgkmcnt(0)
	v_add_f32_e32 v112, v112, v113
	ds_bpermute_b32 v113, v119, v112
	s_waitcnt lgkmcnt(0)
	v_add_f32_e32 v240, v112, v113
	v_lshlrev_b64 v[238:239], 6, v[178:179]
	v_lshl_add_u64 v[238:239], s[82:83], 0, v[238:239]
	v_lshl_add_u64 v[238:239], s[6:7], 2, v[238:239]
	s_lshl_b32 s50, s63, 2
	v_lshl_add_u64 v[238:239], v[238:239], 0, s[50:51]
	s_and_b64 vcc, exec, s[42:43]
	v_mov_b32_e32 v112, 1.0
	s_cbranch_vccnz .LBB0_911
	ds_read_b32 v112, v213 offset:10304

; __device__ __forceinline__ unsigned cvt_pk_bf16(float lo, float hi) { f32x2 v = {lo, hi}; bf16x2_t b = __builtin_convertvector(v, bf16x2_t); return __builtin_bit_cast(unsigned, b); }
;     __device__ __forceinline__ void operator()(const f32x4 (&acc)[2][2][4][2], const Unit& u, int wr, int wc, int fr, int fq) const {
;     ...
;                         const f32x4 v0 = b0 + acc[ai][bj][m][0] * sc, v1 = b1 + acc[ai][bj][m][1] * sc;
;                         if (out != nullptr) { *(f32x4*)(out + off) = v0; *(f32x4*)(out + off + 4) = v1; }
;                         part += (v0[0] * v0[0] + v0[1] * v0[1]) + (v0[2] * v0[2] + v0[3] * v0[3]) + (v1[0] * v1[0] + v1[1] * v1[1]) + (v1[2] * v1[2] + v1[3] * v1[3]);
;                         if (ssq_o1 != nullptr) {
;                             u32x4 w; w.x = cvt_pk_bf16(v0[0], v0[1]); w.y = cvt_pk_bf16(v0[2], v0[3]); w.z = cvt_pk_bf16(v1[0], v1[1]); w.w = cvt_pk_bf16(v1[2], v1[3]);
;                             *(u32x4*)(O + off) = w;
;                         }
;                     }
;                     part += __shfl_xor(part, 16); part += __shfl_xor(part, 32);
;                     if (fq == 0 && ssq_o1 != nullptr) ssq_o1[(size_t)row * 16 + u.pn * 4 + wc] = part;
.LBB0_919:
	v_mul_f32_e32 v109, v109, v109
	v_mul_f32_e32 v101, v101, v101
	v_fmac_f32_e32 v109, v108, v108
	v_mul_f32_e32 v108, v111, v111
	v_fmac_f32_e32 v101, v100, v100
	v_mul_f32_e32 v100, v103, v103
	v_fmac_f32_e32 v108, v110, v110
	v_mul_f32_e32 v105, v105, v105
	v_fmac_f32_e32 v100, v102, v102
	v_mul_f32_e32 v97, v97, v97
	v_add_f32_e32 v108, v109, v108
	v_fmac_f32_e32 v105, v104, v104
	v_add_f32_e32 v100, v101, v100
	v_fmac_f32_e32 v97, v96, v96
	v_add_f32_e32 v104, v105, v108
	v_mul_f32_e32 v105, v107, v107
	v_add_f32_e32 v96, v97, v100
	v_mul_f32_e32 v97, v99, v99
	v_fmac_f32_e32 v105, v106, v106
	v_fmac_f32_e32 v97, v98, v98
	v_add_f32_e32 v104, v105, v104
	v_add_f32_e32 v96, v97, v96
	v_add_f32_e32 v96, v104, v96
	ds_bpermute_b32 v97, v118, v96
	s_waitcnt lgkmcnt(0)
	v_add_f32_e32 v96, v96, v97
	ds_bpermute_b32 v97, v119, v96
	s_waitcnt lgkmcnt(0)
	v_add_f32_e32 v241, v96, v97
	s_and_b64 vcc, exec, s[42:43]
	v_mov_b32_e32 v96, 1.0
	s_cbranch_vccnz .LBB0_923
	ds_read_b32 v96, v213 offset:10368

; __device__ __forceinline__ unsigned cvt_pk_bf16(float lo, float hi) { f32x2 v = {lo, hi}; bf16x2_t b = __builtin_convertvector(v, bf16x2_t); return __builtin_bit_cast(unsigned, b); }
;     __device__ __forceinline__ void operator()(const f32x4 (&acc)[2][2][4][2], const Unit& u, int wr, int wc, int fr, int fq) const {
;     ...
;                         const f32x4 v0 = b0 + acc[ai][bj][m][0] * sc, v1 = b1 + acc[ai][bj][m][1] * sc;
;                         if (out != nullptr) { *(f32x4*)(out + off) = v0; *(f32x4*)(out + off + 4) = v1; }
;                         part += (v0[0] * v0[0] + v0[1] * v0[1]) + (v0[2] * v0[2] + v0[3] * v0[3]) + (v1[0] * v1[0] + v1[1] * v1[1]) + (v1[2] * v1[2] + v1[3] * v1[3]);
;                         if (ssq_o1 != nullptr) {
;                             u32x4 w; w.x = cvt_pk_bf16(v0[0], v0[1]); w.y = cvt_pk_bf16(v0[2], v0[3]); w.z = cvt_pk_bf16(v1[0], v1[1]); w.w = cvt_pk_bf16(v1[2], v1[3]);
;                             *(u32x4*)(O + off) = w;
;                         }
;                     }
;                     part += __shfl_xor(part, 16); part += __shfl_xor(part, 32);
;                     if (fq == 0 && ssq_o1 != nullptr) ssq_o1[(size_t)row * 16 + u.pn * 4 + wc] = part;
.LBB0_931:
	v_mul_f32_e32 v93, v93, v93
	v_mul_f32_e32 v85, v85, v85
	v_fmac_f32_e32 v93, v92, v92
	v_mul_f32_e32 v92, v95, v95
	v_fmac_f32_e32 v85, v84, v84
	v_mul_f32_e32 v84, v87, v87
	v_fmac_f32_e32 v92, v94, v94
	v_mul_f32_e32 v89, v89, v89
	v_fmac_f32_e32 v84, v86, v86
	v_mul_f32_e32 v81, v81, v81
	v_add_f32_e32 v92, v93, v92
	v_fmac_f32_e32 v89, v88, v88
	v_add_f32_e32 v84, v85, v84
	v_fmac_f32_e32 v81, v80, v80
	v_add_f32_e32 v88, v89, v92
	v_mul_f32_e32 v89, v91, v91
	v_add_f32_e32 v80, v81, v84
	v_mul_f32_e32 v81, v83, v83
	v_fmac_f32_e32 v89, v90, v90
	v_fmac_f32_e32 v81, v82, v82
	v_add_f32_e32 v88, v89, v88
	v_add_f32_e32 v80, v81, v80
	v_add_f32_e32 v80, v88, v80
	ds_bpermute_b32 v81, v118, v80
	s_waitcnt lgkmcnt(0)
	v_add_f32_e32 v80, v80, v81
	ds_bpermute_b32 v81, v119, v80
	s_waitcnt lgkmcnt(0)
	v_add_f32_e32 v242, v80, v81
	s_and_b64 vcc, exec, s[42:43]
	v_mov_b32_e32 v80, 1.0
	s_cbranch_vccnz .LBB0_935
	ds_read_b32 v80, v213 offset:10432

; __device__ __forceinline__ unsigned cvt_pk_bf16(float lo, float hi) { f32x2 v = {lo, hi}; bf16x2_t b = __builtin_convertvector(v, bf16x2_t); return __builtin_bit_cast(unsigned, b); }
;     __device__ __forceinline__ void operator()(const f32x4 (&acc)[2][2][4][2], const Unit& u, int wr, int wc, int fr, int fq) const {
;     ...
;                         const f32x4 v0 = b0 + acc[ai][bj][m][0] * sc, v1 = b1 + acc[ai][bj][m][1] * sc;
;                         if (out != nullptr) { *(f32x4*)(out + off) = v0; *(f32x4*)(out + off + 4) = v1; }
;                         part += (v0[0] * v0[0] + v0[1] * v0[1]) + (v0[2] * v0[2] + v0[3] * v0[3]) + (v1[0] * v1[0] + v1[1] * v1[1]) + (v1[2] * v1[2] + v1[3] * v1[3]);
;                         if (ssq_o1 != nullptr) {
;                             u32x4 w; w.x = cvt_pk_bf16(v0[0], v0[1]); w.y = cvt_pk_bf16(v0[2], v0[3]); w.z = cvt_pk_bf16(v1[0], v1[1]); w.w = cvt_pk_bf16(v1[2], v1[3]);
;                             *(u32x4*)(O + off) = w;
;                         }
;                     }
;                     part += __shfl_xor(part, 16); part += __shfl_xor(part, 32);
;                     if (fq == 0 && ssq_o1 != nullptr) ssq_o1[(size_t)row * 16 + u.pn * 4 + wc] = part;
.LBB0_943:
	v_mul_f32_e32 v77, v77, v77
	v_mul_f32_e32 v69, v69, v69
	v_fmac_f32_e32 v77, v76, v76
	v_mul_f32_e32 v76, v79, v79
	v_fmac_f32_e32 v69, v68, v68
	v_mul_f32_e32 v68, v71, v71
	v_fmac_f32_e32 v76, v78, v78
	v_mul_f32_e32 v73, v73, v73
	v_fmac_f32_e32 v68, v70, v70
	v_mul_f32_e32 v65, v65, v65
	v_add_f32_e32 v76, v77, v76
	v_fmac_f32_e32 v73, v72, v72
	v_add_f32_e32 v68, v69, v68
	v_fmac_f32_e32 v65, v64, v64
	v_add_f32_e32 v72, v73, v76
	v_mul_f32_e32 v73, v75, v75
	v_add_f32_e32 v64, v65, v68
	v_mul_f32_e32 v65, v67, v67
	v_fmac_f32_e32 v73, v74, v74
	v_fmac_f32_e32 v65, v66, v66
	v_add_f32_e32 v72, v73, v72
	v_add_f32_e32 v64, v65, v64
	v_add_f32_e32 v64, v72, v64
	ds_bpermute_b32 v65, v118, v64
	s_waitcnt lgkmcnt(0)
	v_add_f32_e32 v64, v64, v65
	ds_bpermute_b32 v65, v119, v64
	s_waitcnt lgkmcnt(0)
	v_add_f32_e32 v243, v64, v65
	v_bfe_u32 v244, v206, 4, 2
	v_mov_b32_e32 v245, 0
	v_cmp_eq_u32_e32 vcc, 1, v244
	s_nop 1
	v_cndmask_b32_e32 v240, v240, v241, vcc
	v_cmp_eq_u32_e32 vcc, 2, v244
	s_nop 1
	v_cndmask_b32_e32 v240, v240, v242, vcc
	v_cmp_eq_u32_e32 vcc, 3, v244
	s_nop 1
	v_cndmask_b32_e32 v240, v240, v243, vcc
	v_lshlrev_b32_e32 v244, 10, v244
	v_lshl_add_u64 v[238:239], v[238:239], 0, v[244:245]
	s_cmp_lg_u64 s[76:77], 0
	s_cbranch_scc0 .Lssq_skip_3
	global_store_dword v[238:239], v240, off
.Lssq_skip_3:
	v_add_u32_e32 v102, 0x80, v178
	v_ashrrev_i32_e32 v103, 31, v102
	s_waitcnt lgkmcnt(0)
	v_lshlrev_b64 v[64:65], 11, v[102:103]
	v_add_u32_e32 v100, 0x90, v178
	v_lshl_add_u64 v[64:65], v[176:177], 0, v[64:65]
	v_ashrrev_i32_e32 v101, 31, v100
	global_load_dwordx4 v[92:95], v[64:65], off
	global_load_dwordx4 v[88:91], v[64:65], off offset:256
	v_lshlrev_b64 v[64:65], 11, v[100:101]
	v_add_u32_e32 v98, 0xa0, v178
	v_lshl_add_u64 v[64:65], v[176:177], 0, v[64:65]
	v_ashrrev_i32_e32 v99, 31, v98
	global_load_dwordx4 v[84:87], v[64:65], off
	global_load_dwordx4 v[80:83], v[64:65], off offset:256
	v_lshlrev_b64 v[64:65], 11, v[98:99]
	v_add_u32_e32 v96, 0xb0, v178
	v_lshl_add_u64 v[64:65], v[176:177], 0, v[64:65]
	v_ashrrev_i32_e32 v97, 31, v96
	global_load_dwordx4 v[76:79], v[64:65], off
	global_load_dwordx4 v[72:75], v[64:65], off offset:256
	v_lshlrev_b64 v[64:65], 11, v[96:97]
	v_lshl_add_u64 v[64:65], v[176:177], 0, v[64:65]
	global_load_dwordx4 v[68:71], v[64:65], off
	s_nop 0
	global_load_dwordx4 v[64:67], v[64:65], off offset:256
	s_and_b64 vcc, exec, s[42:43]
	v_mov_b32_e32 v106, 1.0
	s_cbranch_vccnz .LBB0_947
	ds_read_b32 v106, v214

; __device__ __forceinline__ unsigned cvt_pk_bf16(float lo, float hi) { f32x2 v = {lo, hi}; bf16x2_t b = __builtin_convertvector(v, bf16x2_t); return __builtin_bit_cast(unsigned, b); }
;     __device__ __forceinline__ void operator()(const f32x4 (&acc)[2][2][4][2], const Unit& u, int wr, int wc, int fr, int fq) const {
;     ...
;                         const f32x4 v0 = b0 + acc[ai][bj][m][0] * sc, v1 = b1 + acc[ai][bj][m][1] * sc;
;                         if (out != nullptr) { *(f32x4*)(out + off) = v0; *(f32x4*)(out + off + 4) = v1; }
;                         part += (v0[0] * v0[0] + v0[1] * v0[1]) + (v0[2] * v0[2] + v0[3] * v0[3]) + (v1[0] * v1[0] + v1[1] * v1[1]) + (v1[2] * v1[2] + v1[3] * v1[3]);
;                         if (ssq_o1 != nullptr) {
;                             u32x4 w; w.x = cvt_pk_bf16(v0[0], v0[1]); w.y = cvt_pk_bf16(v0[2], v0[3]); w.z = cvt_pk_bf16(v1[0], v1[1]); w.w = cvt_pk_bf16(v1[2], v1[3]);
;                             *(u32x4*)(O + off) = w;
;                         }
;                     }
;                     part += __shfl_xor(part, 16); part += __shfl_xor(part, 32);
;                     if (fq == 0 && ssq_o1 != nullptr) ssq_o1[(size_t)row * 16 + u.pn * 4 + wc] = part;
.LBB0_955:
	v_mul_f32_e32 v61, v61, v61
	v_mul_f32_e32 v53, v53, v53
	v_fmac_f32_e32 v61, v60, v60
	v_mul_f32_e32 v60, v63, v63
	v_fmac_f32_e32 v53, v52, v52
	v_mul_f32_e32 v52, v55, v55
	v_fmac_f32_e32 v60, v62, v62
	v_mul_f32_e32 v57, v57, v57
	v_fmac_f32_e32 v52, v54, v54
	v_mul_f32_e32 v49, v49, v49
	v_add_f32_e32 v60, v61, v60
	v_fmac_f32_e32 v57, v56, v56
	v_add_f32_e32 v52, v53, v52
	v_fmac_f32_e32 v49, v48, v48
	v_add_f32_e32 v56, v57, v60
	v_mul_f32_e32 v57, v59, v59
	v_add_f32_e32 v48, v49, v52
	v_mul_f32_e32 v49, v51, v51
	v_fmac_f32_e32 v57, v58, v58
	v_fmac_f32_e32 v49, v50, v50
	v_add_f32_e32 v56, v57, v56
	v_add_f32_e32 v48, v49, v48
	v_add_f32_e32 v48, v56, v48
	ds_bpermute_b32 v49, v118, v48
	s_waitcnt lgkmcnt(0)
	v_add_f32_e32 v48, v48, v49
	ds_bpermute_b32 v49, v119, v48
	s_waitcnt lgkmcnt(0)
	v_add_f32_e32 v240, v48, v49
	v_lshlrev_b64 v[238:239], 6, v[102:103]
	v_lshl_add_u64 v[238:239], s[82:83], 0, v[238:239]
	v_lshl_add_u64 v[238:239], s[6:7], 2, v[238:239]
	s_lshl_b32 s50, s63, 2
	v_lshl_add_u64 v[238:239], v[238:239], 0, s[50:51]
	s_and_b64 vcc, exec, s[42:43]
	v_mov_b32_e32 v50, 1.0
	s_cbranch_vccnz .LBB0_959
	ds_read_b32 v50, v213 offset:10816

; __device__ __forceinline__ unsigned cvt_pk_bf16(float lo, float hi) { f32x2 v = {lo, hi}; bf16x2_t b = __builtin_convertvector(v, bf16x2_t); return __builtin_bit_cast(unsigned, b); }
;     __device__ __forceinline__ void operator()(const f32x4 (&acc)[2][2][4][2], const Unit& u, int wr, int wc, int fr, int fq) const {
;     ...
;                         const f32x4 v0 = b0 + acc[ai][bj][m][0] * sc, v1 = b1 + acc[ai][bj][m][1] * sc;
;                         if (out != nullptr) { *(f32x4*)(out + off) = v0; *(f32x4*)(out + off + 4) = v1; }
;                         part += (v0[0] * v0[0] + v0[1] * v0[1]) + (v0[2] * v0[2] + v0[3] * v0[3]) + (v1[0] * v1[0] + v1[1] * v1[1]) + (v1[2] * v1[2] + v1[3] * v1[3]);
;                         if (ssq_o1 != nullptr) {
;                             u32x4 w; w.x = cvt_pk_bf16(v0[0], v0[1]); w.y = cvt_pk_bf16(v0[2], v0[3]); w.z = cvt_pk_bf16(v1[0], v1[1]); w.w = cvt_pk_bf16(v1[2], v1[3]);
;                             *(u32x4*)(O + off) = w;
;                         }
;                     }
;                     part += __shfl_xor(part, 16); part += __shfl_xor(part, 32);
;                     if (fq == 0 && ssq_o1 != nullptr) ssq_o1[(size_t)row * 16 + u.pn * 4 + wc] = part;
.LBB0_967:
	v_mul_f32_e32 v45, v45, v45
	v_mul_f32_e32 v37, v37, v37
	v_fmac_f32_e32 v45, v44, v44
	v_mul_f32_e32 v44, v47, v47
	v_fmac_f32_e32 v37, v36, v36
	v_mul_f32_e32 v36, v39, v39
	v_fmac_f32_e32 v44, v46, v46
	v_mul_f32_e32 v41, v41, v41
	v_fmac_f32_e32 v36, v38, v38
	v_mul_f32_e32 v33, v33, v33
	v_add_f32_e32 v44, v45, v44
	v_fmac_f32_e32 v41, v40, v40
	v_add_f32_e32 v36, v37, v36
	v_fmac_f32_e32 v33, v32, v32
	v_add_f32_e32 v40, v41, v44
	v_mul_f32_e32 v41, v43, v43
	v_add_f32_e32 v32, v33, v36
	v_mul_f32_e32 v33, v35, v35
	v_fmac_f32_e32 v41, v42, v42
	v_fmac_f32_e32 v33, v34, v34
	v_add_f32_e32 v40, v41, v40
	v_add_f32_e32 v32, v33, v32
	v_add_f32_e32 v32, v40, v32
	ds_bpermute_b32 v33, v118, v32
	s_waitcnt lgkmcnt(0)
	v_add_f32_e32 v32, v32, v33
	ds_bpermute_b32 v33, v119, v32
	s_waitcnt lgkmcnt(0)
	v_add_f32_e32 v241, v32, v33
	s_and_b64 vcc, exec, s[42:43]
	v_mov_b32_e32 v34, 1.0
	s_cbranch_vccnz .LBB0_971
	ds_read_b32 v34, v213 offset:10880

; __device__ __forceinline__ unsigned cvt_pk_bf16(float lo, float hi) { f32x2 v = {lo, hi}; bf16x2_t b = __builtin_convertvector(v, bf16x2_t); return __builtin_bit_cast(unsigned, b); }
;     __device__ __forceinline__ void operator()(const f32x4 (&acc)[2][2][4][2], const Unit& u, int wr, int wc, int fr, int fq) const {
;     ...
;                         const f32x4 v0 = b0 + acc[ai][bj][m][0] * sc, v1 = b1 + acc[ai][bj][m][1] * sc;
;                         if (out != nullptr) { *(f32x4*)(out + off) = v0; *(f32x4*)(out + off + 4) = v1; }
;                         part += (v0[0] * v0[0] + v0[1] * v0[1]) + (v0[2] * v0[2] + v0[3] * v0[3]) + (v1[0] * v1[0] + v1[1] * v1[1]) + (v1[2] * v1[2] + v1[3] * v1[3]);
;                         if (ssq_o1 != nullptr) {
;                             u32x4 w; w.x = cvt_pk_bf16(v0[0], v0[1]); w.y = cvt_pk_bf16(v0[2], v0[3]); w.z = cvt_pk_bf16(v1[0], v1[1]); w.w = cvt_pk_bf16(v1[2], v1[3]);
;                             *(u32x4*)(O + off) = w;
;                         }
;                     }
;                     part += __shfl_xor(part, 16); part += __shfl_xor(part, 32);
;                     if (fq == 0 && ssq_o1 != nullptr) ssq_o1[(size_t)row * 16 + u.pn * 4 + wc] = part;
.LBB0_979:
	v_mul_f32_e32 v29, v29, v29
	v_mul_f32_e32 v21, v21, v21
	v_fmac_f32_e32 v29, v28, v28
	v_mul_f32_e32 v28, v31, v31
	v_fmac_f32_e32 v21, v20, v20
	v_mul_f32_e32 v20, v23, v23
	v_fmac_f32_e32 v28, v30, v30
	v_mul_f32_e32 v25, v25, v25
	v_fmac_f32_e32 v20, v22, v22
	v_mul_f32_e32 v17, v17, v17
	v_add_f32_e32 v28, v29, v28
	v_fmac_f32_e32 v25, v24, v24
	v_add_f32_e32 v20, v21, v20
	v_fmac_f32_e32 v17, v16, v16
	v_add_f32_e32 v24, v25, v28
	v_mul_f32_e32 v25, v27, v27
	v_add_f32_e32 v16, v17, v20
	v_mul_f32_e32 v17, v19, v19
	v_fmac_f32_e32 v25, v26, v26
	v_fmac_f32_e32 v17, v18, v18
	v_add_f32_e32 v24, v25, v24
	v_add_f32_e32 v16, v17, v16
	v_add_f32_e32 v16, v24, v16
	ds_bpermute_b32 v17, v118, v16
	s_waitcnt lgkmcnt(0)
	v_add_f32_e32 v16, v16, v17
	ds_bpermute_b32 v17, v119, v16
	s_waitcnt lgkmcnt(0)
	v_add_f32_e32 v242, v16, v17
	s_and_b64 vcc, exec, s[42:43]
	v_mov_b32_e32 v18, 1.0
	s_cbranch_vccnz .LBB0_983
	ds_read_b32 v18, v213 offset:10944

; __device__ __forceinline__ unsigned cvt_pk_bf16(float lo, float hi) { f32x2 v = {lo, hi}; bf16x2_t b = __builtin_convertvector(v, bf16x2_t); return __builtin_bit_cast(unsigned, b); }
;     __device__ __forceinline__ void operator()(const f32x4 (&acc)[2][2][4][2], const Unit& u, int wr, int wc, int fr, int fq) const {
;     ...
;                         const f32x4 v0 = b0 + acc[ai][bj][m][0] * sc, v1 = b1 + acc[ai][bj][m][1] * sc;
;                         if (out != nullptr) { *(f32x4*)(out + off) = v0; *(f32x4*)(out + off + 4) = v1; }
;                         part += (v0[0] * v0[0] + v0[1] * v0[1]) + (v0[2] * v0[2] + v0[3] * v0[3]) + (v1[0] * v1[0] + v1[1] * v1[1]) + (v1[2] * v1[2] + v1[3] * v1[3]);
;                         if (ssq_o1 != nullptr) {
;                             u32x4 w; w.x = cvt_pk_bf16(v0[0], v0[1]); w.y = cvt_pk_bf16(v0[2], v0[3]); w.z = cvt_pk_bf16(v1[0], v1[1]); w.w = cvt_pk_bf16(v1[2], v1[3]);
;                             *(u32x4*)(O + off) = w;
;                         }
;                     }
;                     part += __shfl_xor(part, 16); part += __shfl_xor(part, 32);
;                     if (fq == 0 && ssq_o1 != nullptr) ssq_o1[(size_t)row * 16 + u.pn * 4 + wc] = part;
.LBB0_991:
	v_mul_f32_e32 v13, v13, v13
	v_mul_f32_e32 v5, v5, v5
	v_fmac_f32_e32 v13, v12, v12
	v_mul_f32_e32 v12, v15, v15
	v_fmac_f32_e32 v5, v4, v4
	v_mul_f32_e32 v4, v7, v7
	v_fmac_f32_e32 v12, v14, v14
	v_mul_f32_e32 v9, v9, v9
	v_fmac_f32_e32 v4, v6, v6
	v_mul_f32_e32 v1, v1, v1
	v_add_f32_e32 v12, v13, v12
	v_fmac_f32_e32 v9, v8, v8
	v_add_f32_e32 v4, v5, v4
	v_fmac_f32_e32 v1, v0, v0
	v_add_f32_e32 v8, v9, v12
	v_mul_f32_e32 v9, v11, v11
	v_add_f32_e32 v0, v1, v4
	v_mul_f32_e32 v1, v3, v3
	v_fmac_f32_e32 v9, v10, v10
	v_fmac_f32_e32 v1, v2, v2
	v_add_f32_e32 v8, v9, v8
	v_add_f32_e32 v0, v1, v0
	v_add_f32_e32 v0, v8, v0
	ds_bpermute_b32 v1, v118, v0
	s_waitcnt lgkmcnt(0)
	v_add_f32_e32 v0, v0, v1
	ds_bpermute_b32 v1, v119, v0
	s_waitcnt lgkmcnt(0)
	v_add_f32_e32 v243, v0, v1
	v_bfe_u32 v244, v206, 4, 2
	v_mov_b32_e32 v245, 0
	v_cmp_eq_u32_e32 vcc, 1, v244
	s_nop 1
	v_cndmask_b32_e32 v240, v240, v241, vcc
	v_cmp_eq_u32_e32 vcc, 2, v244
	s_nop 1
	v_cndmask_b32_e32 v240, v240, v242, vcc
	v_cmp_eq_u32_e32 vcc, 3, v244
	s_nop 1
	v_cndmask_b32_e32 v240, v240, v243, vcc
	v_lshlrev_b32_e32 v244, 10, v244
	v_lshl_add_u64 v[238:239], v[238:239], 0, v[244:245]
	s_cmp_lg_u64 s[76:77], 0
	s_cbranch_scc0 .Lssq_skip_7
	global_store_dword v[238:239], v240, off
.Lssq_skip_7:
	s_andn2_b64 vcc, exec, s[40:41]
	s_mov_b64 s[6:7], -1
	s_cbranch_vccnz .LBB0_882
	s_andn2_b64 vcc, exec, s[70:71]
	s_cbranch_vccnz .LBB0_881
	s_barrier
	s_branch .LBB0_881
